# residual (down/out-proj) epilogue: base rows L2-prefetched by dummy LDS-DMA in a dedicated K-loop copy, on the non-GEMM latency stack
# baseline (speedup 1.0000x reference)
; #define PG8_STAGE(bufoff, gbase, voff) do { glds_s((const char*)(gbase), (voff), ldsb + (bufoff)); glds_s((const char*)(gbase) + rstep, (voff), ldsb + (bufoff) + 8192u); } while (0)
; #define PG8_LDA(dst, b, h) do { _Pragma("unroll") for (int m = 0; m < 4; ++m) _Pragma("unroll") for (int k = 0; k < 2; ++k) dst[m][k] = *(const LAS bf16x8*)(lds + PG8_SA(b, h) + aoff + m * 2048 + k * 1024); } while (0)
; #define PG8_LDB(dst, b, h) do { _Pragma("unroll") for (int n = 0; n < 2; ++n) _Pragma("unroll") for (int k = 0; k < 2; ++k) dst[n][k] = *(const LAS bf16x8*)(lds + PG8_SB(b, h) + boff + n * 2048 + k * 1024); } while (0)
; #define PG8_MMA(ai, bj, At, Bt) do { __builtin_amdgcn_s_setprio(1); _Pragma("unroll") for (int m = 0; m < 4; ++m) _Pragma("unroll") for (int n = 0; n < 2; ++n) _Pragma("unroll") for (int k = 0; k < 2; ++k) \
;         acc[ai][bj][m][n] = __builtin_amdgcn_mfma_f32_16x16x32_bf16(Bt[n][k], At[m][k], acc[ai][bj][m][n], 0, 0, 0); __builtin_amdgcn_s_setprio(0); } while (0)
; #define PG8_WAIT_V(n) asm volatile("s_waitcnt vmcnt(" #n ")" ::: "memory")
; #define PG8_WAIT_L(n) asm volatile("s_waitcnt lgkmcnt(" #n ")" ::: "memory")
; #define PG8_BAR __builtin_amdgcn_s_barrier()
; #define PG8_SCHED __builtin_amdgcn_sched_barrier(0)
; template <class Epi, class Sched>
; __device__ __forceinline__ void gemm_phase(LAS unsigned char* lds, const Gemm g, const Sched& S, const Epi& E, const int tid) {
;     ...
;             PG8_LDB(B0, 1, 0); PG8_LDB(B1, 1, 1); PG8_SCHED; PG8_LDA(At, 1, 0); PG8_STAGE(PG8_SA(0, 1), a2 + hstep, voffA);
;             if (relax) PG8_WAIT_V(16); else PG8_WAIT_V(8);
;             PG8_WAIT_L(0); PG8_BAR; PG8_MMA(0, 0, At, B0); PG8_MMA(0, 1, At, B1); PG8_BAR; PG8_SCHED;
;             PG8_LDA(At, 1, 1); PG8_STAGE(PG8_SB(1, 0), b3, voffB); PG8_STAGE(PG8_SB(1, 1), b3 + hstep, voffB); PG8_STAGE(PG8_SA(1, 0), a3, voffA);
;             PG8_WAIT_V(8); PG8_WAIT_L(0); PG8_BAR; PG8_MMA(1, 0, At, B0); PG8_MMA(1, 1, At, B1); PG8_BAR; PG8_SCHED;
.LBB0_199:
	s_add_u32 s2, s2, 0x180
	s_waitcnt lgkmcnt(0)
	s_addc_u32 s3, s3, 0
	s_add_u32 s6, s0, 0x180
	s_addc_u32 s7, s1, 0
	s_barrier
	s_setprio 1
	s_waitcnt lgkmcnt(7)
	v_mfma_f32_16x16x32_bf16 v[0:3], v[66:69], v[122:125], v[0:3]
	s_waitcnt lgkmcnt(6)
	v_mfma_f32_16x16x32_bf16 v[142:145], v[74:77], v[130:133], v[0:3]
	v_mfma_f32_16x16x32_bf16 v[0:3], v[226:229], v[122:125], v[4:7]
	s_waitcnt vmcnt(32)
	v_mfma_f32_16x16x32_bf16 v[134:137], v[230:233], v[130:133], v[0:3]
	s_waitcnt lgkmcnt(5)
	v_mfma_f32_16x16x32_bf16 v[0:3], v[66:69], v[106:109], v[8:11]
	s_waitcnt lgkmcnt(4)
	v_mfma_f32_16x16x32_bf16 v[126:129], v[74:77], v[114:117], v[0:3]
	v_mfma_f32_16x16x32_bf16 v[0:3], v[226:229], v[106:109], v[12:15]
	v_mfma_f32_16x16x32_bf16 v[118:121], v[230:233], v[114:117], v[0:3]
	s_waitcnt lgkmcnt(3)
	v_mfma_f32_16x16x32_bf16 v[0:3], v[66:69], v[90:93], v[16:19]
	s_waitcnt lgkmcnt(2)
	v_mfma_f32_16x16x32_bf16 v[110:113], v[74:77], v[98:101], v[0:3]
	v_mfma_f32_16x16x32_bf16 v[0:3], v[226:229], v[90:93], v[20:23]
	v_mfma_f32_16x16x32_bf16 v[102:105], v[230:233], v[98:101], v[0:3]
	s_waitcnt lgkmcnt(1)
	v_mfma_f32_16x16x32_bf16 v[0:3], v[66:69], v[70:73], v[24:27]
	s_waitcnt lgkmcnt(0)
	v_mfma_f32_16x16x32_bf16 v[94:97], v[74:77], v[78:81], v[0:3]
	v_mfma_f32_16x16x32_bf16 v[0:3], v[226:229], v[70:73], v[28:31]
	v_mfma_f32_16x16x32_bf16 v[82:85], v[230:233], v[78:81], v[0:3]
	s_setprio 0
	s_setprio 1
	v_mfma_f32_16x16x32_bf16 v[0:3], v[210:213], v[122:125], v[32:35]
	v_mfma_f32_16x16x32_bf16 v[146:149], v[214:217], v[130:133], v[0:3]
	v_mfma_f32_16x16x32_bf16 v[0:3], v[218:221], v[122:125], v[36:39]
	v_mfma_f32_16x16x32_bf16 v[138:141], v[222:225], v[130:133], v[0:3]
	v_mfma_f32_16x16x32_bf16 v[0:3], v[210:213], v[106:109], v[40:43]
	v_mfma_f32_16x16x32_bf16 v[130:133], v[214:217], v[114:117], v[0:3]
	v_mfma_f32_16x16x32_bf16 v[0:3], v[218:221], v[106:109], v[44:47]
	v_mfma_f32_16x16x32_bf16 v[122:125], v[222:225], v[114:117], v[0:3]
	v_mfma_f32_16x16x32_bf16 v[0:3], v[210:213], v[90:93], v[48:51]
	v_mfma_f32_16x16x32_bf16 v[114:117], v[214:217], v[98:101], v[0:3]
	v_mfma_f32_16x16x32_bf16 v[0:3], v[218:221], v[90:93], v[52:55]
	v_mfma_f32_16x16x32_bf16 v[106:109], v[222:225], v[98:101], v[0:3]
	v_mfma_f32_16x16x32_bf16 v[0:3], v[210:213], v[70:73], v[56:59]
	v_mfma_f32_16x16x32_bf16 v[98:101], v[214:217], v[78:81], v[0:3]
	v_mfma_f32_16x16x32_bf16 v[0:3], v[218:221], v[70:73], v[60:63]
	v_mfma_f32_16x16x32_bf16 v[90:93], v[222:225], v[78:81], v[0:3]
	s_setprio 0
	s_barrier
	s_nop 4
	ds_read_b128 v[0:3], v250 offset:49152
	ds_read_b128 v[4:7], v250 offset:50176
	ds_read_b128 v[8:11], v250 offset:51200
	ds_read_b128 v[12:15], v250 offset:52224
	ds_read_b128 v[16:19], v250 offset:53248
	ds_read_b128 v[26:29], v250 offset:54272
	ds_read_b128 v[236:239], v250 offset:55296
	ds_read_b128 v[20:23], v250 offset:56320
	s_mov_b32 m0, s59
	s_nop 0
	global_load_lds_dwordx4 v246, s[6:7]
	s_add_u32 s6, s6, s28
	s_addc_u32 s7, s7, s29
	s_mov_b32 m0, s60
	s_nop 0
	global_load_lds_dwordx4 v246, s[6:7]
	s_add_u32 s6, s85, 0x180
	s_addc_u32 s7, s96, 0
	s_mov_b32 m0, s63
	s_nop 0
	global_load_lds_dwordx4 v246, s[6:7]
	s_add_u32 s6, s6, s28
	s_addc_u32 s7, s7, s29
	s_mov_b32 m0, s64
	s_nop 0
	global_load_lds_dwordx4 v246, s[6:7]
	s_mov_b32 m0, s61
	s_nop 0
	global_load_lds_dwordx4 v245, s[2:3]
	s_add_u32 s6, s2, s28
	s_addc_u32 s7, s3, s29
	s_mov_b32 m0, s62
	s_nop 0
	global_load_lds_dwordx4 v245, s[6:7]
	s_waitcnt vmcnt(8)
	s_waitcnt lgkmcnt(0)
	s_barrier
	s_setprio 1
	s_waitcnt lgkmcnt(7)
	v_mfma_f32_16x16x32_bf16 v[30:33], v[66:69], v[0:3], v[150:153]
	s_waitcnt lgkmcnt(6)
	v_mfma_f32_16x16x32_bf16 v[78:81], v[74:77], v[4:7], v[30:33]
	v_mfma_f32_16x16x32_bf16 v[30:33], v[226:229], v[0:3], v[154:157]
	v_mfma_f32_16x16x32_bf16 v[70:73], v[230:233], v[4:7], v[30:33]
	s_waitcnt lgkmcnt(5)
	v_mfma_f32_16x16x32_bf16 v[30:33], v[66:69], v[8:11], v[158:161]
	s_waitcnt lgkmcnt(4)
	v_mfma_f32_16x16x32_bf16 v[62:65], v[74:77], v[12:15], v[30:33]
	v_mfma_f32_16x16x32_bf16 v[30:33], v[226:229], v[8:11], v[162:165]
	v_mfma_f32_16x16x32_bf16 v[54:57], v[230:233], v[12:15], v[30:33]
	s_waitcnt lgkmcnt(3)
	v_mfma_f32_16x16x32_bf16 v[30:33], v[66:69], v[16:19], v[166:169]
	s_waitcnt lgkmcnt(2)
	v_mfma_f32_16x16x32_bf16 v[46:49], v[74:77], v[26:29], v[30:33]
	v_mfma_f32_16x16x32_bf16 v[30:33], v[226:229], v[16:19], v[170:173]
	v_mfma_f32_16x16x32_bf16 v[38:41], v[230:233], v[26:29], v[30:33]
	s_waitcnt lgkmcnt(1)
	v_mfma_f32_16x16x32_bf16 v[30:33], v[66:69], v[236:239], v[174:177]
	v_mfma_f32_16x16x32_bf16 v[34:37], v[226:229], v[236:239], v[86:89]
	s_waitcnt lgkmcnt(0)
	v_mfma_f32_16x16x32_bf16 v[30:33], v[74:77], v[20:23], v[30:33]
	v_mfma_f32_16x16x32_bf16 v[226:229], v[230:233], v[20:23], v[34:37]
	s_setprio 0
	s_setprio 1
	v_mfma_f32_16x16x32_bf16 v[34:37], v[210:213], v[0:3], v[178:181]
	v_mfma_f32_16x16x32_bf16 v[0:3], v[218:221], v[0:3], v[182:185]
	v_mfma_f32_16x16x32_bf16 v[74:77], v[222:225], v[4:7], v[0:3]
	v_mfma_f32_16x16x32_bf16 v[0:3], v[210:213], v[8:11], v[186:189]
	v_mfma_f32_16x16x32_bf16 v[66:69], v[214:217], v[12:15], v[0:3]
	v_mfma_f32_16x16x32_bf16 v[0:3], v[218:221], v[8:11], v[190:193]
	v_mfma_f32_16x16x32_bf16 v[58:61], v[222:225], v[12:15], v[0:3]
	v_mfma_f32_16x16x32_bf16 v[0:3], v[210:213], v[16:19], v[194:197]
	v_mfma_f32_16x16x32_bf16 v[50:53], v[214:217], v[26:29], v[0:3]
	v_mfma_f32_16x16x32_bf16 v[0:3], v[218:221], v[16:19], v[198:201]
	v_mfma_f32_16x16x32_bf16 v[42:45], v[222:225], v[26:29], v[0:3]
	v_mfma_f32_16x16x32_bf16 v[0:3], v[210:213], v[236:239], v[202:205]
	v_mfma_f32_16x16x32_bf16 v[86:89], v[214:217], v[4:7], v[34:37]
	v_mfma_f32_16x16x32_bf16 v[34:37], v[214:217], v[20:23], v[0:3]
	v_mfma_f32_16x16x32_bf16 v[0:3], v[218:221], v[236:239], v[206:209]
	v_mfma_f32_16x16x32_bf16 v[26:29], v[222:225], v[20:23], v[0:3]
	s_setprio 0
	s_barrier
	s_add_u32 s85, s0, 0x200
	s_addc_u32 s96, s1, 0
	s_mov_b32 s97, 4
	s_cmp_eq_u32 s47, 1
	s_cbranch_scc1 .Lk1_entry
; #define PG8_STAGE(bufoff, gbase, voff) do { glds_s((const char*)(gbase), (voff), ldsb + (bufoff)); glds_s((const char*)(gbase) + rstep, (voff), ldsb + (bufoff) + 8192u); } while (0)
; #define PG8_LDA(dst, b, h) do { _Pragma("unroll") for (int m = 0; m < 4; ++m) _Pragma("unroll") for (int k = 0; k < 2; ++k) dst[m][k] = *(const LAS bf16x8*)(lds + PG8_SA(b, h) + aoff + m * 2048 + k * 1024); } while (0)
; #define PG8_LDB(dst, b, h) do { _Pragma("unroll") for (int n = 0; n < 2; ++n) _Pragma("unroll") for (int k = 0; k < 2; ++k) dst[n][k] = *(const LAS bf16x8*)(lds + PG8_SB(b, h) + boff + n * 2048 + k * 1024); } while (0)
; #define PG8_MMA(ai, bj, At, Bt) do { __builtin_amdgcn_s_setprio(1); _Pragma("unroll") for (int m = 0; m < 4; ++m) _Pragma("unroll") for (int n = 0; n < 2; ++n) _Pragma("unroll") for (int k = 0; k < 2; ++k) \
;         acc[ai][bj][m][n] = __builtin_amdgcn_mfma_f32_16x16x32_bf16(Bt[n][k], At[m][k], acc[ai][bj][m][n], 0, 0, 0); __builtin_amdgcn_s_setprio(0); } while (0)
; #define PG8_WAIT_V(n) asm volatile("s_waitcnt vmcnt(" #n ")" ::: "memory")
; #define PG8_WAIT_L(n) asm volatile("s_waitcnt lgkmcnt(" #n ")" ::: "memory")
; #define PG8_BAR __builtin_amdgcn_s_barrier()
; #define PG8_SCHED __builtin_amdgcn_sched_barrier(0)
; template <class Epi, class Sched>
; __device__ __forceinline__ void gemm_phase(LAS unsigned char* lds, const Gemm g, const Sched& S, const Epi& E, const int tid) {
;     ...
;             PG8_LDB(B0, 0, 0); PG8_LDB(B1, 0, 1); PG8_SCHED; PG8_LDA(At, 0, 0); if (!relax) PG8_STAGE(PG8_SA(1, 1), a1 + hstep, voffA);
;             if (relax) PG8_WAIT_V(16); else PG8_WAIT_V(8);
;             PG8_WAIT_L(0); PG8_BAR; PG8_MMA(0, 0, At, B0); PG8_MMA(0, 1, At, B1); PG8_BAR; PG8_SCHED;
;             PG8_LDA(At, 0, 1); PG8_STAGE(PG8_SB(0, 0), b2, voffB); PG8_STAGE(PG8_SB(0, 1), b2 + hstep, voffB); PG8_STAGE(PG8_SA(0, 0), a2, voffA);
;             if (relax) PG8_WAIT_V(16); else PG8_WAIT_V(8);
;             PG8_WAIT_L(0); PG8_BAR; PG8_MMA(1, 0, At, B0); PG8_MMA(1, 1, At, B1); PG8_BAR; PG8_SCHED;
.LBB0_200:
	s_add_u32 s0, s2, 0x80
	s_nop 0
	ds_read_b128 v[0:3], v234
	ds_read_b128 v[4:7], v234 offset:1024
	ds_read_b128 v[8:11], v234 offset:2048
	ds_read_b128 v[12:15], v234 offset:3072
	ds_read_b128 v[16:19], v251
	ds_read_b128 v[20:23], v251 offset:1024
	ds_read_b128 v[150:153], v251 offset:2048
	ds_read_b128 v[154:157], v251 offset:3072
	s_addc_u32 s1, s3, 0
	s_cmp_eq_u32 s42, s97
	s_cselect_b32 s8, s80, s0
	s_cselect_b32 s9, s81, s1
	s_cselect_b32 s40, s82, s85
	s_cselect_b32 s41, s83, s96
	s_add_u32 s0, s8, 0x80
	s_addc_u32 s1, s9, 0
	s_add_u32 s6, s40, 0x80
	s_addc_u32 s7, s41, 0
	ds_read_b128 v[158:161], v250
	ds_read_b128 v[162:165], v250 offset:1024
	ds_read_b128 v[166:169], v250 offset:2048
	ds_read_b128 v[170:173], v250 offset:3072
	ds_read_b128 v[174:177], v250 offset:4096
	ds_read_b128 v[178:181], v250 offset:5120
	ds_read_b128 v[182:185], v250 offset:6144
	ds_read_b128 v[186:189], v250 offset:7168
	s_add_u32 s44, s2, s30
	s_addc_u32 s45, s3, s31
	s_mov_b32 m0, s65
	s_nop 0
	global_load_lds_dwordx4 v245, s[44:45]
	s_add_u32 s44, s44, s28
	s_addc_u32 s45, s45, s29
	s_mov_b32 m0, s86
	s_nop 0
	global_load_lds_dwordx4 v245, s[44:45]
	s_waitcnt vmcnt(8)
	s_waitcnt lgkmcnt(0)
	s_barrier
	s_setprio 1
	s_waitcnt lgkmcnt(7)
	v_mfma_f32_16x16x32_bf16 v[142:145], v[0:3], v[158:161], v[142:145]
	v_mfma_f32_16x16x32_bf16 v[134:137], v[8:11], v[158:161], v[134:137]
	s_waitcnt lgkmcnt(5)
	v_mfma_f32_16x16x32_bf16 v[126:129], v[0:3], v[166:169], v[126:129]
	v_mfma_f32_16x16x32_bf16 v[118:121], v[8:11], v[166:169], v[118:121]
	s_waitcnt lgkmcnt(3)
	v_mfma_f32_16x16x32_bf16 v[110:113], v[0:3], v[174:177], v[110:113]
	v_mfma_f32_16x16x32_bf16 v[102:105], v[8:11], v[174:177], v[102:105]
	s_waitcnt lgkmcnt(1)
	v_mfma_f32_16x16x32_bf16 v[94:97], v[0:3], v[182:185], v[94:97]
	v_mfma_f32_16x16x32_bf16 v[82:85], v[8:11], v[182:185], v[82:85]
	v_mfma_f32_16x16x32_bf16 v[142:145], v[4:7], v[162:165], v[142:145]
	v_mfma_f32_16x16x32_bf16 v[134:137], v[12:15], v[162:165], v[134:137]
	v_mfma_f32_16x16x32_bf16 v[126:129], v[4:7], v[170:173], v[126:129]
	v_mfma_f32_16x16x32_bf16 v[118:121], v[12:15], v[170:173], v[118:121]
	v_mfma_f32_16x16x32_bf16 v[110:113], v[4:7], v[178:181], v[110:113]
	v_mfma_f32_16x16x32_bf16 v[102:105], v[12:15], v[178:181], v[102:105]
	s_waitcnt lgkmcnt(0)
	v_mfma_f32_16x16x32_bf16 v[94:97], v[4:7], v[186:189], v[94:97]
	v_mfma_f32_16x16x32_bf16 v[82:85], v[12:15], v[186:189], v[82:85]
	s_setprio 0
	s_setprio 1
	v_mfma_f32_16x16x32_bf16 v[146:149], v[16:19], v[158:161], v[146:149]
	v_mfma_f32_16x16x32_bf16 v[138:141], v[150:153], v[158:161], v[138:141]
	v_mfma_f32_16x16x32_bf16 v[130:133], v[16:19], v[166:169], v[130:133]
	v_mfma_f32_16x16x32_bf16 v[122:125], v[150:153], v[166:169], v[122:125]
	v_mfma_f32_16x16x32_bf16 v[114:117], v[16:19], v[174:177], v[114:117]
	v_mfma_f32_16x16x32_bf16 v[106:109], v[150:153], v[174:177], v[106:109]
	v_mfma_f32_16x16x32_bf16 v[98:101], v[16:19], v[182:185], v[98:101]
	v_mfma_f32_16x16x32_bf16 v[90:93], v[150:153], v[182:185], v[90:93]
	v_mfma_f32_16x16x32_bf16 v[146:149], v[20:23], v[162:165], v[146:149]
	v_mfma_f32_16x16x32_bf16 v[138:141], v[154:157], v[162:165], v[138:141]
	v_mfma_f32_16x16x32_bf16 v[130:133], v[20:23], v[170:173], v[130:133]
	v_mfma_f32_16x16x32_bf16 v[122:125], v[154:157], v[170:173], v[122:125]
	v_mfma_f32_16x16x32_bf16 v[114:117], v[20:23], v[178:181], v[114:117]
	v_mfma_f32_16x16x32_bf16 v[106:109], v[154:157], v[178:181], v[106:109]
	v_mfma_f32_16x16x32_bf16 v[98:101], v[20:23], v[186:189], v[98:101]
	v_mfma_f32_16x16x32_bf16 v[90:93], v[154:157], v[186:189], v[90:93]
	s_setprio 0
	s_barrier
	s_add_u32 s44, s40, s28
	ds_read_b128 v[158:161], v250 offset:16384
	ds_read_b128 v[162:165], v250 offset:17408
	ds_read_b128 v[166:169], v250 offset:18432
	ds_read_b128 v[170:173], v250 offset:19456
	ds_read_b128 v[174:177], v250 offset:20480
	ds_read_b128 v[178:181], v250 offset:21504
	ds_read_b128 v[182:185], v250 offset:22528
	ds_read_b128 v[186:189], v250 offset:23552
	s_addc_u32 s45, s41, s29
	s_mov_b32 m0, s50
	s_nop 0
	global_load_lds_dwordx4 v246, s[40:41]
	s_add_u32 s40, s40, s30
	s_mov_b32 m0, s51
	s_nop 0
	global_load_lds_dwordx4 v246, s[44:45]
	s_addc_u32 s41, s41, s31
	s_mov_b32 m0, s52
	s_nop 0
	global_load_lds_dwordx4 v246, s[40:41]
	s_add_u32 s44, s40, s28
	s_addc_u32 s45, s41, s29
	s_mov_b32 m0, s53
	s_nop 0
	global_load_lds_dwordx4 v246, s[44:45]
	s_add_u32 s44, s8, s28
	s_mov_b32 m0, s49
	s_nop 0
	global_load_lds_dwordx4 v245, s[8:9]
	s_addc_u32 s45, s9, s29
	s_mov_b32 m0, s54
	s_nop 0
	global_load_lds_dwordx4 v245, s[44:45]
	s_waitcnt vmcnt(8)
	s_waitcnt lgkmcnt(0)
	s_barrier
; #define PG8_STAGE(bufoff, gbase, voff) do { glds_s((const char*)(gbase), (voff), ldsb + (bufoff)); glds_s((const char*)(gbase) + rstep, (voff), ldsb + (bufoff) + 8192u); } while (0)
; #define PG8_LDA(dst, b, h) do { _Pragma("unroll") for (int m = 0; m < 4; ++m) _Pragma("unroll") for (int k = 0; k < 2; ++k) dst[m][k] = *(const LAS bf16x8*)(lds + PG8_SA(b, h) + aoff + m * 2048 + k * 1024); } while (0)
; #define PG8_LDB(dst, b, h) do { _Pragma("unroll") for (int n = 0; n < 2; ++n) _Pragma("unroll") for (int k = 0; k < 2; ++k) dst[n][k] = *(const LAS bf16x8*)(lds + PG8_SB(b, h) + boff + n * 2048 + k * 1024); } while (0)
; #define PG8_MMA(ai, bj, At, Bt) do { __builtin_amdgcn_s_setprio(1); _Pragma("unroll") for (int m = 0; m < 4; ++m) _Pragma("unroll") for (int n = 0; n < 2; ++n) _Pragma("unroll") for (int k = 0; k < 2; ++k) \
;         acc[ai][bj][m][n] = __builtin_amdgcn_mfma_f32_16x16x32_bf16(Bt[n][k], At[m][k], acc[ai][bj][m][n], 0, 0, 0); __builtin_amdgcn_s_setprio(0); } while (0)
; #define PG8_WAIT_V(n) asm volatile("s_waitcnt vmcnt(" #n ")" ::: "memory")
; #define PG8_WAIT_L(n) asm volatile("s_waitcnt lgkmcnt(" #n ")" ::: "memory")
; #define PG8_BAR __builtin_amdgcn_s_barrier()
; #define PG8_SCHED __builtin_amdgcn_sched_barrier(0)
; template <class Epi, class Sched>
; __device__ __forceinline__ void gemm_phase(LAS unsigned char* lds, const Gemm g, const Sched& S, const Epi& E, const int tid) {
;     ...
;             PG8_WAIT_L(0); PG8_BAR; PG8_MMA(1, 0, At, B0); PG8_MMA(1, 1, At, B1); PG8_BAR; PG8_SCHED;
;             PG8_LDB(B0, 1, 0); PG8_LDB(B1, 1, 1); PG8_SCHED; PG8_LDA(At, 1, 0); PG8_STAGE(PG8_SA(0, 1), a2 + hstep, voffA);
;             if (relax) PG8_WAIT_V(16); else PG8_WAIT_V(8);
;             PG8_WAIT_L(0); PG8_BAR; PG8_MMA(0, 0, At, B0); PG8_MMA(0, 1, At, B1); PG8_BAR; PG8_SCHED;
	s_setprio 1
	s_waitcnt lgkmcnt(7)
	v_mfma_f32_16x16x32_bf16 v[78:81], v[0:3], v[158:161], v[78:81]
	v_mfma_f32_16x16x32_bf16 v[70:73], v[8:11], v[158:161], v[70:73]
	s_waitcnt lgkmcnt(5)
	v_mfma_f32_16x16x32_bf16 v[62:65], v[0:3], v[166:169], v[62:65]
	v_mfma_f32_16x16x32_bf16 v[54:57], v[8:11], v[166:169], v[54:57]
	s_waitcnt lgkmcnt(3)
	v_mfma_f32_16x16x32_bf16 v[46:49], v[0:3], v[174:177], v[46:49]
	v_mfma_f32_16x16x32_bf16 v[38:41], v[8:11], v[174:177], v[38:41]
	s_waitcnt lgkmcnt(1)
	v_mfma_f32_16x16x32_bf16 v[0:3], v[0:3], v[182:185], v[30:33]
	v_mfma_f32_16x16x32_bf16 v[78:81], v[4:7], v[162:165], v[78:81]
	v_mfma_f32_16x16x32_bf16 v[70:73], v[12:15], v[162:165], v[70:73]
	v_mfma_f32_16x16x32_bf16 v[62:65], v[4:7], v[170:173], v[62:65]
	v_mfma_f32_16x16x32_bf16 v[54:57], v[12:15], v[170:173], v[54:57]
	v_mfma_f32_16x16x32_bf16 v[46:49], v[4:7], v[178:181], v[46:49]
	v_mfma_f32_16x16x32_bf16 v[38:41], v[12:15], v[178:181], v[38:41]
	s_waitcnt lgkmcnt(0)
	v_mfma_f32_16x16x32_bf16 v[0:3], v[4:7], v[186:189], v[0:3]
	v_mfma_f32_16x16x32_bf16 v[4:7], v[8:11], v[182:185], v[226:229]
	v_mfma_f32_16x16x32_bf16 v[4:7], v[12:15], v[186:189], v[4:7]
	s_setprio 0
	s_setprio 1
	v_mfma_f32_16x16x32_bf16 v[30:33], v[16:19], v[166:169], v[66:69]
	v_mfma_f32_16x16x32_bf16 v[66:69], v[20:23], v[170:173], v[30:33]
	v_mfma_f32_16x16x32_bf16 v[30:33], v[150:153], v[166:169], v[58:61]
	v_mfma_f32_16x16x32_bf16 v[58:61], v[154:157], v[170:173], v[30:33]
	v_mfma_f32_16x16x32_bf16 v[30:33], v[16:19], v[174:177], v[50:53]
	v_mfma_f32_16x16x32_bf16 v[8:11], v[16:19], v[158:161], v[86:89]
	v_mfma_f32_16x16x32_bf16 v[50:53], v[20:23], v[178:181], v[30:33]
	v_mfma_f32_16x16x32_bf16 v[30:33], v[150:153], v[174:177], v[42:45]
	v_mfma_f32_16x16x32_bf16 v[16:19], v[16:19], v[182:185], v[34:37]
	v_mfma_f32_16x16x32_bf16 v[8:11], v[20:23], v[162:165], v[8:11]
	v_mfma_f32_16x16x32_bf16 v[12:15], v[150:153], v[158:161], v[74:77]
	v_mfma_f32_16x16x32_bf16 v[42:45], v[154:157], v[178:181], v[30:33]
	v_mfma_f32_16x16x32_bf16 v[16:19], v[20:23], v[186:189], v[16:19]
	v_mfma_f32_16x16x32_bf16 v[20:23], v[150:153], v[182:185], v[26:29]
	v_mfma_f32_16x16x32_bf16 v[12:15], v[154:157], v[162:165], v[12:15]
	v_mfma_f32_16x16x32_bf16 v[20:23], v[154:157], v[186:189], v[20:23]
	s_setprio 0
	s_barrier
	ds_read_b128 v[24:27], v252
	ds_read_b128 v[28:31], v252 offset:1024
	ds_read_b128 v[34:37], v252 offset:2048
	ds_read_b128 v[74:77], v252 offset:3072
	ds_read_b128 v[150:153], v240
	ds_read_b128 v[154:157], v240 offset:1024
	ds_read_b128 v[158:161], v240 offset:2048
	ds_read_b128 v[162:165], v240 offset:3072
	ds_read_b128 v[86:89], v250 offset:32768
	ds_read_b128 v[166:169], v250 offset:33792
	ds_read_b128 v[170:173], v250 offset:34816
	ds_read_b128 v[174:177], v250 offset:35840
	ds_read_b128 v[178:181], v250 offset:36864
	ds_read_b128 v[182:185], v250 offset:37888
	ds_read_b128 v[186:189], v250 offset:38912
	ds_read_b128 v[190:193], v250 offset:39936
	s_add_u32 s8, s8, s30
	s_addc_u32 s9, s9, s31
	s_mov_b32 m0, s55
	s_nop 0
	global_load_lds_dwordx4 v245, s[8:9]
	s_add_u32 s8, s8, s28
	s_addc_u32 s9, s9, s29
	s_mov_b32 m0, s56
	s_nop 0
	global_load_lds_dwordx4 v245, s[8:9]
	s_waitcnt vmcnt(8)
	s_waitcnt lgkmcnt(0)
	s_barrier
	s_setprio 1
	s_waitcnt lgkmcnt(7)
	v_mfma_f32_16x16x32_bf16 v[142:145], v[24:27], v[86:89], v[142:145]
	v_mfma_f32_16x16x32_bf16 v[134:137], v[34:37], v[86:89], v[134:137]
	s_waitcnt lgkmcnt(5)
	v_mfma_f32_16x16x32_bf16 v[126:129], v[24:27], v[170:173], v[126:129]
	v_mfma_f32_16x16x32_bf16 v[118:121], v[34:37], v[170:173], v[118:121]
	s_waitcnt lgkmcnt(3)
	v_mfma_f32_16x16x32_bf16 v[110:113], v[24:27], v[178:181], v[110:113]
	v_mfma_f32_16x16x32_bf16 v[102:105], v[34:37], v[178:181], v[102:105]
	s_waitcnt lgkmcnt(1)
	v_mfma_f32_16x16x32_bf16 v[94:97], v[24:27], v[186:189], v[94:97]
	v_mfma_f32_16x16x32_bf16 v[82:85], v[34:37], v[186:189], v[82:85]
	v_mfma_f32_16x16x32_bf16 v[142:145], v[28:31], v[166:169], v[142:145]
	v_mfma_f32_16x16x32_bf16 v[134:137], v[74:77], v[166:169], v[134:137]
	v_mfma_f32_16x16x32_bf16 v[126:129], v[28:31], v[174:177], v[126:129]
	v_mfma_f32_16x16x32_bf16 v[118:121], v[74:77], v[174:177], v[118:121]
	v_mfma_f32_16x16x32_bf16 v[110:113], v[28:31], v[182:185], v[110:113]
	v_mfma_f32_16x16x32_bf16 v[102:105], v[74:77], v[182:185], v[102:105]
	s_waitcnt lgkmcnt(0)
	v_mfma_f32_16x16x32_bf16 v[94:97], v[28:31], v[190:193], v[94:97]
	v_mfma_f32_16x16x32_bf16 v[82:85], v[74:77], v[190:193], v[82:85]
	s_setprio 0
	s_setprio 1
	v_mfma_f32_16x16x32_bf16 v[146:149], v[150:153], v[86:89], v[146:149]
	v_mfma_f32_16x16x32_bf16 v[86:89], v[158:161], v[86:89], v[138:141]
	v_mfma_f32_16x16x32_bf16 v[138:141], v[162:165], v[166:169], v[86:89]
	v_mfma_f32_16x16x32_bf16 v[86:89], v[150:153], v[170:173], v[130:133]
	v_mfma_f32_16x16x32_bf16 v[130:133], v[154:157], v[174:177], v[86:89]
	v_mfma_f32_16x16x32_bf16 v[86:89], v[158:161], v[170:173], v[122:125]
	v_mfma_f32_16x16x32_bf16 v[122:125], v[162:165], v[174:177], v[86:89]
	v_mfma_f32_16x16x32_bf16 v[86:89], v[150:153], v[178:181], v[114:117]
	v_mfma_f32_16x16x32_bf16 v[114:117], v[154:157], v[182:185], v[86:89]
	v_mfma_f32_16x16x32_bf16 v[86:89], v[158:161], v[178:181], v[106:109]
	v_mfma_f32_16x16x32_bf16 v[106:109], v[162:165], v[182:185], v[86:89]
	v_mfma_f32_16x16x32_bf16 v[86:89], v[150:153], v[186:189], v[98:101]
	v_mfma_f32_16x16x32_bf16 v[98:101], v[154:157], v[190:193], v[86:89]
	v_mfma_f32_16x16x32_bf16 v[86:89], v[158:161], v[186:189], v[90:93]
	v_mfma_f32_16x16x32_bf16 v[146:149], v[154:157], v[166:169], v[146:149]
	v_mfma_f32_16x16x32_bf16 v[90:93], v[162:165], v[190:193], v[86:89]
	s_setprio 0
	s_barrier
; #define PG8_STAGE(bufoff, gbase, voff) do { glds_s((const char*)(gbase), (voff), ldsb + (bufoff)); glds_s((const char*)(gbase) + rstep, (voff), ldsb + (bufoff) + 8192u); } while (0)
; #define PG8_LDA(dst, b, h) do { _Pragma("unroll") for (int m = 0; m < 4; ++m) _Pragma("unroll") for (int k = 0; k < 2; ++k) dst[m][k] = *(const LAS bf16x8*)(lds + PG8_SA(b, h) + aoff + m * 2048 + k * 1024); } while (0)
; #define PG8_MMA(ai, bj, At, Bt) do { __builtin_amdgcn_s_setprio(1); _Pragma("unroll") for (int m = 0; m < 4; ++m) _Pragma("unroll") for (int n = 0; n < 2; ++n) _Pragma("unroll") for (int k = 0; k < 2; ++k) \
;         acc[ai][bj][m][n] = __builtin_amdgcn_mfma_f32_16x16x32_bf16(Bt[n][k], At[m][k], acc[ai][bj][m][n], 0, 0, 0); __builtin_amdgcn_s_setprio(0); } while (0)
; #define PG8_WAIT_V(n) asm volatile("s_waitcnt vmcnt(" #n ")" ::: "memory")
; #define PG8_WAIT_L(n) asm volatile("s_waitcnt lgkmcnt(" #n ")" ::: "memory")
; #define PG8_BAR __builtin_amdgcn_s_barrier()
; #define PG8_SCHED __builtin_amdgcn_sched_barrier(0)
; template <class Epi, class Sched>
; __device__ __forceinline__ void gemm_phase(LAS unsigned char* lds, const Gemm g, const Sched& S, const Epi& E, const int tid) {
;     ...
;             PG8_LDA(At, 1, 1); PG8_STAGE(PG8_SB(1, 0), b3, voffB); PG8_STAGE(PG8_SB(1, 1), b3 + hstep, voffB); PG8_STAGE(PG8_SA(1, 0), a3, voffA);
;             PG8_WAIT_V(8); PG8_WAIT_L(0); PG8_BAR; PG8_MMA(1, 0, At, B0); PG8_MMA(1, 1, At, B1); PG8_BAR; PG8_SCHED;
;         }
	ds_read_b128 v[166:169], v250 offset:49152
	ds_read_b128 v[170:173], v250 offset:50176
	ds_read_b128 v[174:177], v250 offset:51200
	ds_read_b128 v[178:181], v250 offset:52224
	ds_read_b128 v[182:185], v250 offset:53248
	ds_read_b128 v[186:189], v250 offset:54272
	ds_read_b128 v[190:193], v250 offset:55296
	ds_read_b128 v[194:197], v250 offset:56320
	s_mov_b32 m0, s59
	s_nop 0
	global_load_lds_dwordx4 v246, s[6:7]
	s_add_u32 s6, s6, s28
	s_addc_u32 s7, s7, s29
	s_mov_b32 m0, s60
	s_nop 0
	global_load_lds_dwordx4 v246, s[6:7]
	s_add_u32 s6, s40, 0x80
	s_addc_u32 s7, s41, 0
	s_mov_b32 m0, s63
	s_nop 0
	global_load_lds_dwordx4 v246, s[6:7]
	s_add_u32 s6, s6, s28
	s_addc_u32 s7, s7, s29
	s_mov_b32 m0, s64
	s_nop 0
	global_load_lds_dwordx4 v246, s[6:7]
	s_mov_b32 m0, s61
	s_nop 0
	global_load_lds_dwordx4 v245, s[0:1]
	s_add_u32 s0, s0, s28
	s_addc_u32 s1, s1, s29
	s_mov_b32 m0, s62
	s_nop 0
	global_load_lds_dwordx4 v245, s[0:1]
	s_waitcnt vmcnt(8)
	s_waitcnt lgkmcnt(0)
	s_barrier
	s_setprio 1
	s_waitcnt lgkmcnt(7)
	v_mfma_f32_16x16x32_bf16 v[78:81], v[24:27], v[166:169], v[78:81]
	s_waitcnt lgkmcnt(5)
	v_mfma_f32_16x16x32_bf16 v[62:65], v[24:27], v[174:177], v[62:65]
	s_waitcnt lgkmcnt(3)
	v_mfma_f32_16x16x32_bf16 v[46:49], v[24:27], v[182:185], v[46:49]
	s_waitcnt lgkmcnt(1)
	v_mfma_f32_16x16x32_bf16 v[0:3], v[24:27], v[190:193], v[0:3]
	v_mfma_f32_16x16x32_bf16 v[78:81], v[28:31], v[170:173], v[78:81]
	v_mfma_f32_16x16x32_bf16 v[70:73], v[34:37], v[166:169], v[70:73]
	v_mfma_f32_16x16x32_bf16 v[62:65], v[28:31], v[178:181], v[62:65]
	v_mfma_f32_16x16x32_bf16 v[54:57], v[34:37], v[174:177], v[54:57]
	v_mfma_f32_16x16x32_bf16 v[46:49], v[28:31], v[186:189], v[46:49]
	v_mfma_f32_16x16x32_bf16 v[38:41], v[34:37], v[182:185], v[38:41]
	s_waitcnt lgkmcnt(0)
	v_mfma_f32_16x16x32_bf16 v[30:33], v[28:31], v[194:197], v[0:3]
	v_mfma_f32_16x16x32_bf16 v[0:3], v[34:37], v[190:193], v[4:7]
	v_mfma_f32_16x16x32_bf16 v[70:73], v[74:77], v[170:173], v[70:73]
	v_mfma_f32_16x16x32_bf16 v[54:57], v[74:77], v[178:181], v[54:57]
	v_mfma_f32_16x16x32_bf16 v[38:41], v[74:77], v[186:189], v[38:41]
	v_mfma_f32_16x16x32_bf16 v[226:229], v[74:77], v[194:197], v[0:3]
	s_setprio 0
	s_setprio 1
	v_mfma_f32_16x16x32_bf16 v[0:3], v[150:153], v[166:169], v[8:11]
	v_mfma_f32_16x16x32_bf16 v[86:89], v[154:157], v[170:173], v[0:3]
	v_mfma_f32_16x16x32_bf16 v[0:3], v[158:161], v[166:169], v[12:15]
	v_mfma_f32_16x16x32_bf16 v[74:77], v[162:165], v[170:173], v[0:3]
	v_mfma_f32_16x16x32_bf16 v[0:3], v[150:153], v[174:177], v[66:69]
	v_mfma_f32_16x16x32_bf16 v[66:69], v[154:157], v[178:181], v[0:3]
	v_mfma_f32_16x16x32_bf16 v[0:3], v[158:161], v[174:177], v[58:61]
	v_mfma_f32_16x16x32_bf16 v[58:61], v[162:165], v[178:181], v[0:3]
	v_mfma_f32_16x16x32_bf16 v[0:3], v[150:153], v[182:185], v[50:53]
	v_mfma_f32_16x16x32_bf16 v[50:53], v[154:157], v[186:189], v[0:3]
	v_mfma_f32_16x16x32_bf16 v[0:3], v[158:161], v[182:185], v[42:45]
	v_mfma_f32_16x16x32_bf16 v[42:45], v[162:165], v[186:189], v[0:3]
	v_mfma_f32_16x16x32_bf16 v[0:3], v[150:153], v[190:193], v[16:19]
	v_mfma_f32_16x16x32_bf16 v[34:37], v[154:157], v[194:197], v[0:3]
	v_mfma_f32_16x16x32_bf16 v[0:3], v[158:161], v[190:193], v[20:23]
	v_mfma_f32_16x16x32_bf16 v[26:29], v[162:165], v[194:197], v[0:3]
	s_setprio 0
	s_barrier
	s_add_u32 s2, s2, 0x100
	s_addc_u32 s3, s3, 0
	s_add_i32 s0, s97, 2
	s_add_u32 s85, s85, 0x100
	s_addc_u32 s96, s96, 0
	s_cmp_ge_u32 s97, s42
	s_mov_b32 s97, s0
	s_cbranch_scc0 .LBB0_200
.Lk1_exit:
	s_and_b64 vcc, exec, s[68:69]
	s_cbranch_vccz .LBB0_203
	s_barrier

; #define PG8_STAGE(bufoff, gbase, voff) do { glds_s((const char*)(gbase), (voff), ldsb + (bufoff)); glds_s((const char*)(gbase) + rstep, (voff), ldsb + (bufoff) + 8192u); } while (0)
; #define PG8_LDA(dst, b, h) do { _Pragma("unroll") for (int m = 0; m < 4; ++m) _Pragma("unroll") for (int k = 0; k < 2; ++k) dst[m][k] = *(const LAS bf16x8*)(lds + PG8_SA(b, h) + aoff + m * 2048 + k * 1024); } while (0)
; #define PG8_LDB(dst, b, h) do { _Pragma("unroll") for (int n = 0; n < 2; ++n) _Pragma("unroll") for (int k = 0; k < 2; ++k) dst[n][k] = *(const LAS bf16x8*)(lds + PG8_SB(b, h) + boff + n * 2048 + k * 1024); } while (0)
; #define PG8_WAIT_V(n) asm volatile("s_waitcnt vmcnt(" #n ")" ::: "memory")
; #define PG8_WAIT_L(n) asm volatile("s_waitcnt lgkmcnt(" #n ")" ::: "memory")
; #define PG8_BAR __builtin_amdgcn_s_barrier()
;     __device__ __forceinline__ void operator()(const Acc& acc, const Unit& u, int wr, int wc, int fr, int fq) const {
;     ...
;                     for (int bj = 0; bj < 2; ++bj) bs[m][bj] = *(const u32x4*)(Bp + (size_t)(row0 + ai * HALF + m * 16) * DM + col0 + bj * HALF);
;                     if (lnp) st[m] = *(const f32x2*)(stats + (size_t)(row0 + ai * HALF + m * 16) * 2);
; template <class Epi, class Sched>
; __device__ __forceinline__ void gemm_phase(LAS unsigned char* lds, const Gemm g, const Sched& S, const Epi& E, const int tid) {
;     ...
;         for (int t = 0; t < nt; t += 2) {
;             const bool last = (t == nt - 2);
;             const char* a1 = cA + (size_t)(t + 1) * kstep;
;             const char* a2 = last ? nA : cA + (size_t)(t + 2) * kstep; const char* b2 = last ? nB : cB + (size_t)(t + 2) * kstep;
;             const char* a3 = a2 + kstep; const char* b3 = b2 + kstep;
;             const bool relax = (t == 0) && (ui > 0);
;             PG8_LDB(B0, 0, 0); PG8_LDB(B1, 0, 1); PG8_SCHED; PG8_LDA(At, 0, 0); if (!relax) PG8_STAGE(PG8_SA(1, 1), a1 + hstep, voffA);
;             if (relax) PG8_WAIT_V(16); else PG8_WAIT_V(8);
;             PG8_WAIT_L(0); PG8_BAR; PG8_MMA(0, 0, At, B0); PG8_MMA(0, 1, At, B1); PG8_BAR; PG8_SCHED;
;             PG8_LDA(At, 0, 1); PG8_STAGE(PG8_SB(0, 0), b2, voffB); PG8_STAGE(PG8_SB(0, 1), b2 + hstep, voffB); PG8_STAGE(PG8_SA(0, 0), a2, voffA);
;             if (relax) PG8_WAIT_V(16); else PG8_WAIT_V(8);
;             PG8_WAIT_L(0); PG8_BAR; PG8_MMA(1, 0, At, B0); PG8_MMA(1, 1, At, B1); PG8_BAR; PG8_SCHED;
.Lk1_entry:
	s_lshr_b32 s0, s57, 6
	s_lshl_b32 s0, s0, 2
	s_lshr_b32 s1, s87, 4
	s_add_i32 s0, s0, s1
	s_lshl_b32 s0, s0, 5
	s_lshl_b32 s1, s95, 8
	s_add_i32 s0, s0, s1
	s_lshl_b32 s98, s0, 11
	s_lshl_b32 s1, s84, 9
	s_add_u32 s98, s98, s1
	s_add_u32 s98, s98, s14
	s_addc_u32 s99, s15, 0
	v_lshrrev_b32_e32 v242, 5, v244
	v_mul_u32_u24_e32 v242, 0x600, v242
	v_lshl_add_u32 v242, v244, 4, v242
	s_mov_b32 m0, 0x20800
	s_nop 0
	global_load_lds_dwordx4 v242, s[98:99]
.Lk1_loop:
	s_add_u32 s0, s2, 0x80
	s_nop 0
	ds_read_b128 v[0:3], v234
	ds_read_b128 v[4:7], v234 offset:1024
	ds_read_b128 v[8:11], v234 offset:2048
	ds_read_b128 v[12:15], v234 offset:3072
	ds_read_b128 v[16:19], v251
	ds_read_b128 v[20:23], v251 offset:1024
	ds_read_b128 v[150:153], v251 offset:2048
	ds_read_b128 v[154:157], v251 offset:3072
	s_addc_u32 s1, s3, 0
	s_cmp_eq_u32 s42, s97
	s_cselect_b32 s8, s80, s0
	s_cselect_b32 s9, s81, s1
	s_cselect_b32 s40, s82, s85
	s_cselect_b32 s41, s83, s96
	s_add_u32 s0, s8, 0x80
	s_addc_u32 s1, s9, 0
	s_add_u32 s6, s40, 0x80
	s_addc_u32 s7, s41, 0
	ds_read_b128 v[158:161], v250
	ds_read_b128 v[162:165], v250 offset:1024
	ds_read_b128 v[166:169], v250 offset:2048
	ds_read_b128 v[170:173], v250 offset:3072
	ds_read_b128 v[174:177], v250 offset:4096
	ds_read_b128 v[178:181], v250 offset:5120
	ds_read_b128 v[182:185], v250 offset:6144
	ds_read_b128 v[186:189], v250 offset:7168
	s_add_u32 s44, s2, s30
	s_addc_u32 s45, s3, s31
	s_mov_b32 m0, s65
	s_nop 0
	global_load_lds_dwordx4 v245, s[44:45]
	s_add_u32 s44, s44, s28
	s_addc_u32 s45, s45, s29
	s_mov_b32 m0, s86
	s_nop 0
	global_load_lds_dwordx4 v245, s[44:45]
	s_waitcnt vmcnt(9)
	s_waitcnt lgkmcnt(0)
	s_barrier
	s_setprio 1
	s_waitcnt lgkmcnt(7)
	v_mfma_f32_16x16x32_bf16 v[142:145], v[0:3], v[158:161], v[142:145]
	v_mfma_f32_16x16x32_bf16 v[134:137], v[8:11], v[158:161], v[134:137]
	s_waitcnt lgkmcnt(5)
	v_mfma_f32_16x16x32_bf16 v[126:129], v[0:3], v[166:169], v[126:129]
	v_mfma_f32_16x16x32_bf16 v[118:121], v[8:11], v[166:169], v[118:121]
	s_waitcnt lgkmcnt(3)
	v_mfma_f32_16x16x32_bf16 v[110:113], v[0:3], v[174:177], v[110:113]
	v_mfma_f32_16x16x32_bf16 v[102:105], v[8:11], v[174:177], v[102:105]
	s_waitcnt lgkmcnt(1)
	v_mfma_f32_16x16x32_bf16 v[94:97], v[0:3], v[182:185], v[94:97]
	v_mfma_f32_16x16x32_bf16 v[82:85], v[8:11], v[182:185], v[82:85]
	v_mfma_f32_16x16x32_bf16 v[142:145], v[4:7], v[162:165], v[142:145]
	v_mfma_f32_16x16x32_bf16 v[134:137], v[12:15], v[162:165], v[134:137]
	v_mfma_f32_16x16x32_bf16 v[126:129], v[4:7], v[170:173], v[126:129]
	v_mfma_f32_16x16x32_bf16 v[118:121], v[12:15], v[170:173], v[118:121]
	v_mfma_f32_16x16x32_bf16 v[110:113], v[4:7], v[178:181], v[110:113]
	v_mfma_f32_16x16x32_bf16 v[102:105], v[12:15], v[178:181], v[102:105]
	s_waitcnt lgkmcnt(0)
	v_mfma_f32_16x16x32_bf16 v[94:97], v[4:7], v[186:189], v[94:97]
	v_mfma_f32_16x16x32_bf16 v[82:85], v[12:15], v[186:189], v[82:85]
	s_setprio 0
	s_setprio 1
	v_mfma_f32_16x16x32_bf16 v[146:149], v[16:19], v[158:161], v[146:149]
	v_mfma_f32_16x16x32_bf16 v[138:141], v[150:153], v[158:161], v[138:141]
	v_mfma_f32_16x16x32_bf16 v[130:133], v[16:19], v[166:169], v[130:133]
	v_mfma_f32_16x16x32_bf16 v[122:125], v[150:153], v[166:169], v[122:125]
	v_mfma_f32_16x16x32_bf16 v[114:117], v[16:19], v[174:177], v[114:117]
	v_mfma_f32_16x16x32_bf16 v[106:109], v[150:153], v[174:177], v[106:109]
	v_mfma_f32_16x16x32_bf16 v[98:101], v[16:19], v[182:185], v[98:101]
	v_mfma_f32_16x16x32_bf16 v[90:93], v[150:153], v[182:185], v[90:93]
	v_mfma_f32_16x16x32_bf16 v[146:149], v[20:23], v[162:165], v[146:149]
	v_mfma_f32_16x16x32_bf16 v[138:141], v[154:157], v[162:165], v[138:141]
	v_mfma_f32_16x16x32_bf16 v[130:133], v[20:23], v[170:173], v[130:133]
	v_mfma_f32_16x16x32_bf16 v[122:125], v[154:157], v[170:173], v[122:125]
	v_mfma_f32_16x16x32_bf16 v[114:117], v[20:23], v[178:181], v[114:117]
	v_mfma_f32_16x16x32_bf16 v[106:109], v[154:157], v[178:181], v[106:109]
	v_mfma_f32_16x16x32_bf16 v[98:101], v[20:23], v[186:189], v[98:101]
	v_mfma_f32_16x16x32_bf16 v[90:93], v[154:157], v[186:189], v[90:93]
	s_setprio 0
	s_barrier
	s_add_u32 s44, s40, s28
	ds_read_b128 v[158:161], v250 offset:16384
	ds_read_b128 v[162:165], v250 offset:17408
	ds_read_b128 v[166:169], v250 offset:18432
	ds_read_b128 v[170:173], v250 offset:19456
	ds_read_b128 v[174:177], v250 offset:20480
	ds_read_b128 v[178:181], v250 offset:21504
	ds_read_b128 v[182:185], v250 offset:22528
	ds_read_b128 v[186:189], v250 offset:23552
	s_addc_u32 s45, s41, s29
	s_mov_b32 m0, s50
	s_nop 0
	global_load_lds_dwordx4 v246, s[40:41]
	s_add_u32 s40, s40, s30
	s_mov_b32 m0, s51
	s_nop 0
	global_load_lds_dwordx4 v246, s[44:45]
	s_addc_u32 s41, s41, s31
	s_mov_b32 m0, s52
	s_nop 0
	global_load_lds_dwordx4 v246, s[40:41]
	s_add_u32 s44, s40, s28
	s_addc_u32 s45, s41, s29
	s_mov_b32 m0, s53
	s_nop 0
	global_load_lds_dwordx4 v246, s[44:45]
	s_add_u32 s44, s8, s28
	s_mov_b32 m0, s49
	s_nop 0
	global_load_lds_dwordx4 v245, s[8:9]
	s_addc_u32 s45, s9, s29
	s_mov_b32 m0, s54
	s_nop 0
	global_load_lds_dwordx4 v245, s[44:45]
	s_sub_i32 s33, s97, s42
	s_add_i32 s33, s33, 14
	s_max_i32 s33, s33, 0
	s_lshl_b32 s33, s33, 12
	s_add_u32 s44, s98, s33
	s_addc_u32 s45, s99, 0
	s_mov_b32 m0, 0x20800
	s_nop 0
	global_load_lds_dwordx4 v242, s[44:45]
	s_waitcnt vmcnt(10)
	s_waitcnt lgkmcnt(0)
	s_barrier
; #define PG8_STAGE(bufoff, gbase, voff) do { glds_s((const char*)(gbase), (voff), ldsb + (bufoff)); glds_s((const char*)(gbase) + rstep, (voff), ldsb + (bufoff) + 8192u); } while (0)
; #define PG8_LDA(dst, b, h) do { _Pragma("unroll") for (int m = 0; m < 4; ++m) _Pragma("unroll") for (int k = 0; k < 2; ++k) dst[m][k] = *(const LAS bf16x8*)(lds + PG8_SA(b, h) + aoff + m * 2048 + k * 1024); } while (0)
; #define PG8_LDB(dst, b, h) do { _Pragma("unroll") for (int n = 0; n < 2; ++n) _Pragma("unroll") for (int k = 0; k < 2; ++k) dst[n][k] = *(const LAS bf16x8*)(lds + PG8_SB(b, h) + boff + n * 2048 + k * 1024); } while (0)
; #define PG8_MMA(ai, bj, At, Bt) do { __builtin_amdgcn_s_setprio(1); _Pragma("unroll") for (int m = 0; m < 4; ++m) _Pragma("unroll") for (int n = 0; n < 2; ++n) _Pragma("unroll") for (int k = 0; k < 2; ++k) \
;         acc[ai][bj][m][n] = __builtin_amdgcn_mfma_f32_16x16x32_bf16(Bt[n][k], At[m][k], acc[ai][bj][m][n], 0, 0, 0); __builtin_amdgcn_s_setprio(0); } while (0)
; #define PG8_WAIT_V(n) asm volatile("s_waitcnt vmcnt(" #n ")" ::: "memory")
; #define PG8_WAIT_L(n) asm volatile("s_waitcnt lgkmcnt(" #n ")" ::: "memory")
; #define PG8_BAR __builtin_amdgcn_s_barrier()
; #define PG8_SCHED __builtin_amdgcn_sched_barrier(0)
; template <class Epi, class Sched>
; __device__ __forceinline__ void gemm_phase(LAS unsigned char* lds, const Gemm g, const Sched& S, const Epi& E, const int tid) {
;     ...
;             PG8_WAIT_L(0); PG8_BAR; PG8_MMA(1, 0, At, B0); PG8_MMA(1, 1, At, B1); PG8_BAR; PG8_SCHED;
;             PG8_LDB(B0, 1, 0); PG8_LDB(B1, 1, 1); PG8_SCHED; PG8_LDA(At, 1, 0); PG8_STAGE(PG8_SA(0, 1), a2 + hstep, voffA);
;             if (relax) PG8_WAIT_V(16); else PG8_WAIT_V(8);
;             PG8_WAIT_L(0); PG8_BAR; PG8_MMA(0, 0, At, B0); PG8_MMA(0, 1, At, B1); PG8_BAR; PG8_SCHED;
	s_setprio 1
	s_waitcnt lgkmcnt(7)
	v_mfma_f32_16x16x32_bf16 v[78:81], v[0:3], v[158:161], v[78:81]
	v_mfma_f32_16x16x32_bf16 v[70:73], v[8:11], v[158:161], v[70:73]
	s_waitcnt lgkmcnt(5)
	v_mfma_f32_16x16x32_bf16 v[62:65], v[0:3], v[166:169], v[62:65]
	v_mfma_f32_16x16x32_bf16 v[54:57], v[8:11], v[166:169], v[54:57]
	s_waitcnt lgkmcnt(3)
	v_mfma_f32_16x16x32_bf16 v[46:49], v[0:3], v[174:177], v[46:49]
	v_mfma_f32_16x16x32_bf16 v[38:41], v[8:11], v[174:177], v[38:41]
	s_waitcnt lgkmcnt(1)
	v_mfma_f32_16x16x32_bf16 v[0:3], v[0:3], v[182:185], v[30:33]
	v_mfma_f32_16x16x32_bf16 v[78:81], v[4:7], v[162:165], v[78:81]
	v_mfma_f32_16x16x32_bf16 v[70:73], v[12:15], v[162:165], v[70:73]
	v_mfma_f32_16x16x32_bf16 v[62:65], v[4:7], v[170:173], v[62:65]
	v_mfma_f32_16x16x32_bf16 v[54:57], v[12:15], v[170:173], v[54:57]
	v_mfma_f32_16x16x32_bf16 v[46:49], v[4:7], v[178:181], v[46:49]
	v_mfma_f32_16x16x32_bf16 v[38:41], v[12:15], v[178:181], v[38:41]
	s_waitcnt lgkmcnt(0)
	v_mfma_f32_16x16x32_bf16 v[0:3], v[4:7], v[186:189], v[0:3]
	v_mfma_f32_16x16x32_bf16 v[4:7], v[8:11], v[182:185], v[226:229]
	v_mfma_f32_16x16x32_bf16 v[4:7], v[12:15], v[186:189], v[4:7]
	s_setprio 0
	s_setprio 1
	v_mfma_f32_16x16x32_bf16 v[30:33], v[16:19], v[166:169], v[66:69]
	v_mfma_f32_16x16x32_bf16 v[66:69], v[20:23], v[170:173], v[30:33]
	v_mfma_f32_16x16x32_bf16 v[30:33], v[150:153], v[166:169], v[58:61]
	v_mfma_f32_16x16x32_bf16 v[58:61], v[154:157], v[170:173], v[30:33]
	v_mfma_f32_16x16x32_bf16 v[30:33], v[16:19], v[174:177], v[50:53]
	v_mfma_f32_16x16x32_bf16 v[8:11], v[16:19], v[158:161], v[86:89]
	v_mfma_f32_16x16x32_bf16 v[50:53], v[20:23], v[178:181], v[30:33]
	v_mfma_f32_16x16x32_bf16 v[30:33], v[150:153], v[174:177], v[42:45]
	v_mfma_f32_16x16x32_bf16 v[16:19], v[16:19], v[182:185], v[34:37]
	v_mfma_f32_16x16x32_bf16 v[8:11], v[20:23], v[162:165], v[8:11]
	v_mfma_f32_16x16x32_bf16 v[12:15], v[150:153], v[158:161], v[74:77]
	v_mfma_f32_16x16x32_bf16 v[42:45], v[154:157], v[178:181], v[30:33]
	v_mfma_f32_16x16x32_bf16 v[16:19], v[20:23], v[186:189], v[16:19]
	v_mfma_f32_16x16x32_bf16 v[20:23], v[150:153], v[182:185], v[26:29]
	v_mfma_f32_16x16x32_bf16 v[12:15], v[154:157], v[162:165], v[12:15]
	v_mfma_f32_16x16x32_bf16 v[20:23], v[154:157], v[186:189], v[20:23]
	s_setprio 0
	s_barrier
	ds_read_b128 v[24:27], v252
	ds_read_b128 v[28:31], v252 offset:1024
	ds_read_b128 v[34:37], v252 offset:2048
	ds_read_b128 v[74:77], v252 offset:3072
	ds_read_b128 v[150:153], v240
	ds_read_b128 v[154:157], v240 offset:1024
	ds_read_b128 v[158:161], v240 offset:2048
	ds_read_b128 v[162:165], v240 offset:3072
	ds_read_b128 v[86:89], v250 offset:32768
	ds_read_b128 v[166:169], v250 offset:33792
	ds_read_b128 v[170:173], v250 offset:34816
	ds_read_b128 v[174:177], v250 offset:35840
	ds_read_b128 v[178:181], v250 offset:36864
	ds_read_b128 v[182:185], v250 offset:37888
	ds_read_b128 v[186:189], v250 offset:38912
	ds_read_b128 v[190:193], v250 offset:39936
	s_add_u32 s8, s8, s30
	s_addc_u32 s9, s9, s31
	s_mov_b32 m0, s55
	s_nop 0
	global_load_lds_dwordx4 v245, s[8:9]
	s_add_u32 s8, s8, s28
	s_addc_u32 s9, s9, s29
	s_mov_b32 m0, s56
	s_nop 0
	global_load_lds_dwordx4 v245, s[8:9]
	s_waitcnt vmcnt(9)
	s_waitcnt lgkmcnt(0)
	s_barrier
	s_setprio 1
	s_waitcnt lgkmcnt(7)
	v_mfma_f32_16x16x32_bf16 v[142:145], v[24:27], v[86:89], v[142:145]
	v_mfma_f32_16x16x32_bf16 v[134:137], v[34:37], v[86:89], v[134:137]
	s_waitcnt lgkmcnt(5)
	v_mfma_f32_16x16x32_bf16 v[126:129], v[24:27], v[170:173], v[126:129]
	v_mfma_f32_16x16x32_bf16 v[118:121], v[34:37], v[170:173], v[118:121]
	s_waitcnt lgkmcnt(3)
	v_mfma_f32_16x16x32_bf16 v[110:113], v[24:27], v[178:181], v[110:113]
	v_mfma_f32_16x16x32_bf16 v[102:105], v[34:37], v[178:181], v[102:105]
	s_waitcnt lgkmcnt(1)
	v_mfma_f32_16x16x32_bf16 v[94:97], v[24:27], v[186:189], v[94:97]
	v_mfma_f32_16x16x32_bf16 v[82:85], v[34:37], v[186:189], v[82:85]
	v_mfma_f32_16x16x32_bf16 v[142:145], v[28:31], v[166:169], v[142:145]
	v_mfma_f32_16x16x32_bf16 v[134:137], v[74:77], v[166:169], v[134:137]
	v_mfma_f32_16x16x32_bf16 v[126:129], v[28:31], v[174:177], v[126:129]
	v_mfma_f32_16x16x32_bf16 v[118:121], v[74:77], v[174:177], v[118:121]
	v_mfma_f32_16x16x32_bf16 v[110:113], v[28:31], v[182:185], v[110:113]
	v_mfma_f32_16x16x32_bf16 v[102:105], v[74:77], v[182:185], v[102:105]
	s_waitcnt lgkmcnt(0)
	v_mfma_f32_16x16x32_bf16 v[94:97], v[28:31], v[190:193], v[94:97]
	v_mfma_f32_16x16x32_bf16 v[82:85], v[74:77], v[190:193], v[82:85]
	s_setprio 0
	s_setprio 1
	v_mfma_f32_16x16x32_bf16 v[146:149], v[150:153], v[86:89], v[146:149]
	v_mfma_f32_16x16x32_bf16 v[86:89], v[158:161], v[86:89], v[138:141]
	v_mfma_f32_16x16x32_bf16 v[138:141], v[162:165], v[166:169], v[86:89]
	v_mfma_f32_16x16x32_bf16 v[86:89], v[150:153], v[170:173], v[130:133]
	v_mfma_f32_16x16x32_bf16 v[130:133], v[154:157], v[174:177], v[86:89]
	v_mfma_f32_16x16x32_bf16 v[86:89], v[158:161], v[170:173], v[122:125]
	v_mfma_f32_16x16x32_bf16 v[122:125], v[162:165], v[174:177], v[86:89]
	v_mfma_f32_16x16x32_bf16 v[86:89], v[150:153], v[178:181], v[114:117]
	v_mfma_f32_16x16x32_bf16 v[114:117], v[154:157], v[182:185], v[86:89]
	v_mfma_f32_16x16x32_bf16 v[86:89], v[158:161], v[178:181], v[106:109]
	v_mfma_f32_16x16x32_bf16 v[106:109], v[162:165], v[182:185], v[86:89]
	v_mfma_f32_16x16x32_bf16 v[86:89], v[150:153], v[186:189], v[98:101]
	v_mfma_f32_16x16x32_bf16 v[98:101], v[154:157], v[190:193], v[86:89]
	v_mfma_f32_16x16x32_bf16 v[86:89], v[158:161], v[186:189], v[90:93]
	v_mfma_f32_16x16x32_bf16 v[146:149], v[154:157], v[166:169], v[146:149]
	v_mfma_f32_16x16x32_bf16 v[90:93], v[162:165], v[190:193], v[86:89]
	s_setprio 0
	s_barrier
; #define PG8_STAGE(bufoff, gbase, voff) do { glds_s((const char*)(gbase), (voff), ldsb + (bufoff)); glds_s((const char*)(gbase) + rstep, (voff), ldsb + (bufoff) + 8192u); } while (0)
; #define PG8_LDA(dst, b, h) do { _Pragma("unroll") for (int m = 0; m < 4; ++m) _Pragma("unroll") for (int k = 0; k < 2; ++k) dst[m][k] = *(const LAS bf16x8*)(lds + PG8_SA(b, h) + aoff + m * 2048 + k * 1024); } while (0)
; #define PG8_MMA(ai, bj, At, Bt) do { __builtin_amdgcn_s_setprio(1); _Pragma("unroll") for (int m = 0; m < 4; ++m) _Pragma("unroll") for (int n = 0; n < 2; ++n) _Pragma("unroll") for (int k = 0; k < 2; ++k) \
;         acc[ai][bj][m][n] = __builtin_amdgcn_mfma_f32_16x16x32_bf16(Bt[n][k], At[m][k], acc[ai][bj][m][n], 0, 0, 0); __builtin_amdgcn_s_setprio(0); } while (0)
; #define PG8_WAIT_V(n) asm volatile("s_waitcnt vmcnt(" #n ")" ::: "memory")
; #define PG8_WAIT_L(n) asm volatile("s_waitcnt lgkmcnt(" #n ")" ::: "memory")
; #define PG8_BAR __builtin_amdgcn_s_barrier()
; #define PG8_SCHED __builtin_amdgcn_sched_barrier(0)
; template <class Epi, class Sched>
; __device__ __forceinline__ void gemm_phase(LAS unsigned char* lds, const Gemm g, const Sched& S, const Epi& E, const int tid) {
;     ...
;             PG8_LDA(At, 1, 1); PG8_STAGE(PG8_SB(1, 0), b3, voffB); PG8_STAGE(PG8_SB(1, 1), b3 + hstep, voffB); PG8_STAGE(PG8_SA(1, 0), a3, voffA);
;             PG8_WAIT_V(8); PG8_WAIT_L(0); PG8_BAR; PG8_MMA(1, 0, At, B0); PG8_MMA(1, 1, At, B1); PG8_BAR; PG8_SCHED;
;         }
	ds_read_b128 v[166:169], v250 offset:49152
	ds_read_b128 v[170:173], v250 offset:50176
	ds_read_b128 v[174:177], v250 offset:51200
	ds_read_b128 v[178:181], v250 offset:52224
	ds_read_b128 v[182:185], v250 offset:53248
	ds_read_b128 v[186:189], v250 offset:54272
	ds_read_b128 v[190:193], v250 offset:55296
	ds_read_b128 v[194:197], v250 offset:56320
	s_mov_b32 m0, s59
	s_nop 0
	global_load_lds_dwordx4 v246, s[6:7]
	s_add_u32 s6, s6, s28
	s_addc_u32 s7, s7, s29
	s_mov_b32 m0, s60
	s_nop 0
	global_load_lds_dwordx4 v246, s[6:7]
	s_add_u32 s6, s40, 0x80
	s_addc_u32 s7, s41, 0
	s_mov_b32 m0, s63
	s_nop 0
	global_load_lds_dwordx4 v246, s[6:7]
	s_add_u32 s6, s6, s28
	s_addc_u32 s7, s7, s29
	s_mov_b32 m0, s64
	s_nop 0
	global_load_lds_dwordx4 v246, s[6:7]
	s_mov_b32 m0, s61
	s_nop 0
	global_load_lds_dwordx4 v245, s[0:1]
	s_add_u32 s0, s0, s28
	s_addc_u32 s1, s1, s29
	s_mov_b32 m0, s62
	s_nop 0
	global_load_lds_dwordx4 v245, s[0:1]
	s_sub_i32 s33, s97, s42
	s_add_i32 s33, s33, 15
	s_max_i32 s33, s33, 0
	s_lshl_b32 s33, s33, 12
	s_add_u32 s44, s98, s33
	s_addc_u32 s45, s99, 0
	s_mov_b32 m0, 0x20800
	s_nop 0
	global_load_lds_dwordx4 v242, s[44:45]
	s_waitcnt vmcnt(10)
	s_waitcnt lgkmcnt(0)
	s_barrier
	s_setprio 1
	s_waitcnt lgkmcnt(7)
	v_mfma_f32_16x16x32_bf16 v[78:81], v[24:27], v[166:169], v[78:81]
	s_waitcnt lgkmcnt(5)
	v_mfma_f32_16x16x32_bf16 v[62:65], v[24:27], v[174:177], v[62:65]
	s_waitcnt lgkmcnt(3)
	v_mfma_f32_16x16x32_bf16 v[46:49], v[24:27], v[182:185], v[46:49]
	s_waitcnt lgkmcnt(1)
	v_mfma_f32_16x16x32_bf16 v[0:3], v[24:27], v[190:193], v[0:3]
	v_mfma_f32_16x16x32_bf16 v[78:81], v[28:31], v[170:173], v[78:81]
	v_mfma_f32_16x16x32_bf16 v[70:73], v[34:37], v[166:169], v[70:73]
	v_mfma_f32_16x16x32_bf16 v[62:65], v[28:31], v[178:181], v[62:65]
	v_mfma_f32_16x16x32_bf16 v[54:57], v[34:37], v[174:177], v[54:57]
	v_mfma_f32_16x16x32_bf16 v[46:49], v[28:31], v[186:189], v[46:49]
	v_mfma_f32_16x16x32_bf16 v[38:41], v[34:37], v[182:185], v[38:41]
	s_waitcnt lgkmcnt(0)
	v_mfma_f32_16x16x32_bf16 v[30:33], v[28:31], v[194:197], v[0:3]
	v_mfma_f32_16x16x32_bf16 v[0:3], v[34:37], v[190:193], v[4:7]
	v_mfma_f32_16x16x32_bf16 v[70:73], v[74:77], v[170:173], v[70:73]
	v_mfma_f32_16x16x32_bf16 v[54:57], v[74:77], v[178:181], v[54:57]
	v_mfma_f32_16x16x32_bf16 v[38:41], v[74:77], v[186:189], v[38:41]
	v_mfma_f32_16x16x32_bf16 v[226:229], v[74:77], v[194:197], v[0:3]
	s_setprio 0
	s_setprio 1
	v_mfma_f32_16x16x32_bf16 v[0:3], v[150:153], v[166:169], v[8:11]
	v_mfma_f32_16x16x32_bf16 v[86:89], v[154:157], v[170:173], v[0:3]
	v_mfma_f32_16x16x32_bf16 v[0:3], v[158:161], v[166:169], v[12:15]
	v_mfma_f32_16x16x32_bf16 v[74:77], v[162:165], v[170:173], v[0:3]
	v_mfma_f32_16x16x32_bf16 v[0:3], v[150:153], v[174:177], v[66:69]
	v_mfma_f32_16x16x32_bf16 v[66:69], v[154:157], v[178:181], v[0:3]
	v_mfma_f32_16x16x32_bf16 v[0:3], v[158:161], v[174:177], v[58:61]
	v_mfma_f32_16x16x32_bf16 v[58:61], v[162:165], v[178:181], v[0:3]
	v_mfma_f32_16x16x32_bf16 v[0:3], v[150:153], v[182:185], v[50:53]
	v_mfma_f32_16x16x32_bf16 v[50:53], v[154:157], v[186:189], v[0:3]
	v_mfma_f32_16x16x32_bf16 v[0:3], v[158:161], v[182:185], v[42:45]
	v_mfma_f32_16x16x32_bf16 v[42:45], v[162:165], v[186:189], v[0:3]
	v_mfma_f32_16x16x32_bf16 v[0:3], v[150:153], v[190:193], v[16:19]
	v_mfma_f32_16x16x32_bf16 v[34:37], v[154:157], v[194:197], v[0:3]
	v_mfma_f32_16x16x32_bf16 v[0:3], v[158:161], v[190:193], v[20:23]
	v_mfma_f32_16x16x32_bf16 v[26:29], v[162:165], v[194:197], v[0:3]
	s_setprio 0
	s_barrier
	s_add_u32 s2, s2, 0x100
	s_addc_u32 s3, s3, 0
	s_add_i32 s0, s97, 2
	s_add_u32 s85, s85, 0x100
	s_addc_u32 s96, s96, 0
	s_cmp_ge_u32 s97, s42
	s_mov_b32 s97, s0
	s_cbranch_scc0 .Lk1_loop
	v_mov_b32_e32 v242, 0x80
	s_branch .Lk1_exit
